# v34 + pre-armed priority also at the 12 unrolled compute-segment heads (MLA-KV GEMM and one other short-K GEMM)
# baseline (speedup 1.0000x reference)
.LBB0_680:
	s_ashr_i32 s35, s34, 31
	s_lshl_b64 s[2:3], s[34:35], 17
	v_readlane_b32 s6, v251, 63
	s_add_u32 s38, s6, s2
	v_readlane_b32 s2, v252, 0
	s_addc_u32 s39, s2, s3
	s_and_b64 s[2:3], s[0:1], exec
	s_cselect_b32 s59, s39, s49
	s_cselect_b32 s58, s38, s48
	s_ashr_i32 s25, s24, 31
	s_lshl_b64 s[2:3], s[24:25], 17
	s_add_u32 s42, s5, s2
	s_addc_u32 s43, s17, s3
	s_and_b64 s[2:3], s[0:1], exec
	s_cselect_b32 s51, s43, s53
	s_cselect_b32 s50, s42, s52
	s_add_i32 s25, 0, 0x10000
	s_add_i32 s6, 0, 0x14000
	v_add_u32_e32 v96, s25, v148
	v_add_u32_e32 v198, s6, v148
	ds_read_b128 v[0:3], v96
	ds_read_b128 v[4:7], v96 offset:1024
	ds_read_b128 v[8:11], v96 offset:2048
	ds_read_b128 v[12:15], v96 offset:3072
	ds_read_b128 v[16:19], v198
	ds_read_b128 v[20:23], v198 offset:1024
	ds_read_b128 v[24:27], v198 offset:2048
	ds_read_b128 v[28:31], v198 offset:3072
	s_add_u32 s2, s48, 0x10080
	s_addc_u32 s3, s49, 0
	s_add_i32 s56, s18, 0xc000
	v_lshl_add_u64 v[64:65], s[2:3], 0, v[138:139]
	s_mov_b32 m0, s56
	ds_read_b128 v[32:35], v149
	ds_read_b128 v[36:39], v149 offset:1024
	ds_read_b128 v[40:43], v149 offset:2048
	ds_read_b128 v[44:47], v149 offset:3072
	ds_read_b128 v[48:51], v149 offset:4096
	ds_read_b128 v[52:55], v149 offset:5120
	ds_read_b128 v[56:59], v149 offset:6144
	ds_read_b128 v[60:63], v149 offset:7168
	global_load_lds_dwordx4 v[64:65], off
	v_lshl_add_u64 v[64:65], s[2:3], 0, v[142:143]
	s_add_i32 s2, s18, 0xe000
	s_mov_b32 m0, s2
	s_nop 0
	global_load_lds_dwordx4 v[64:65], off
	s_setprio 1
	s_waitcnt vmcnt(8)
	s_waitcnt lgkmcnt(0)
	s_barrier
	v_mfma_f32_16x16x32_bf16 v[64:67], v[0:3], v[32:35], 0
	v_mfma_f32_16x16x32_bf16 v[68:71], v[8:11], v[32:35], 0
	v_mfma_f32_16x16x32_bf16 v[72:75], v[0:3], v[40:43], 0
	v_mfma_f32_16x16x32_bf16 v[76:79], v[8:11], v[40:43], 0
	v_mfma_f32_16x16x32_bf16 v[80:83], v[0:3], v[48:51], 0
	v_mfma_f32_16x16x32_bf16 v[84:87], v[8:11], v[48:51], 0
	v_mfma_f32_16x16x32_bf16 v[88:91], v[0:3], v[56:59], 0
	v_mfma_f32_16x16x32_bf16 v[92:95], v[8:11], v[56:59], 0
	v_mfma_f32_16x16x32_bf16 v[64:67], v[4:7], v[36:39], v[64:67]
	v_mfma_f32_16x16x32_bf16 v[68:71], v[12:15], v[36:39], v[68:71]
	v_mfma_f32_16x16x32_bf16 v[72:75], v[4:7], v[44:47], v[72:75]
	v_mfma_f32_16x16x32_bf16 v[76:79], v[12:15], v[44:47], v[76:79]
	v_mfma_f32_16x16x32_bf16 v[80:83], v[4:7], v[52:55], v[80:83]
	v_mfma_f32_16x16x32_bf16 v[84:87], v[12:15], v[52:55], v[84:87]
	v_mfma_f32_16x16x32_bf16 v[88:91], v[4:7], v[60:63], v[88:91]
	v_mfma_f32_16x16x32_bf16 v[92:95], v[12:15], v[60:63], v[92:95]
	s_setprio 0
	s_setprio 1
	v_mfma_f32_16x16x32_bf16 v[98:101], v[16:19], v[32:35], 0
	v_mfma_f32_16x16x32_bf16 v[32:35], v[24:27], v[32:35], 0
	v_mfma_f32_16x16x32_bf16 v[98:101], v[20:23], v[36:39], v[98:101]
	v_mfma_f32_16x16x32_bf16 v[32:35], v[28:31], v[36:39], v[32:35]
	v_mfma_f32_16x16x32_bf16 v[36:39], v[16:19], v[40:43], 0
	v_mfma_f32_16x16x32_bf16 v[40:43], v[24:27], v[40:43], 0
	v_mfma_f32_16x16x32_bf16 v[36:39], v[20:23], v[44:47], v[36:39]
	v_mfma_f32_16x16x32_bf16 v[40:43], v[28:31], v[44:47], v[40:43]
	v_mfma_f32_16x16x32_bf16 v[44:47], v[16:19], v[48:51], 0
	v_mfma_f32_16x16x32_bf16 v[48:51], v[24:27], v[48:51], 0
	v_mfma_f32_16x16x32_bf16 v[44:47], v[20:23], v[52:55], v[44:47]
	v_mfma_f32_16x16x32_bf16 v[48:51], v[28:31], v[52:55], v[48:51]
	v_mfma_f32_16x16x32_bf16 v[52:55], v[16:19], v[56:59], 0
	v_mfma_f32_16x16x32_bf16 v[56:59], v[24:27], v[56:59], 0
	v_mfma_f32_16x16x32_bf16 v[52:55], v[20:23], v[60:63], v[52:55]
	v_mfma_f32_16x16x32_bf16 v[56:59], v[28:31], v[60:63], v[56:59]
	s_setprio 0
	s_barrier
	s_add_i32 s25, s25, s4
	v_lshl_add_u64 v[146:147], s[52:53], 0, v[140:141]
	s_mov_b64 vcc, 0x100
	s_add_i32 s3, s25, 0x2000
	v_lshl_add_u64 v[130:131], v[146:147], 0, vcc
	s_mov_b32 m0, s25
	v_lshl_add_u64 v[178:179], s[52:53], 0, v[144:145]
	s_add_u32 s60, s52, 0x10100
	ds_read_b128 v[60:63], v149 offset:16384
	ds_read_b128 v[102:105], v149 offset:17408
	ds_read_b128 v[106:109], v149 offset:18432
	ds_read_b128 v[110:113], v149 offset:19456
	ds_read_b128 v[114:117], v149 offset:20480
	ds_read_b128 v[118:121], v149 offset:21504
	ds_read_b128 v[122:125], v149 offset:22528
	ds_read_b128 v[126:129], v149 offset:23552
	global_load_lds_dwordx4 v[130:131], off
	v_lshl_add_u64 v[130:131], v[178:179], 0, vcc
	s_mov_b32 m0, s3
	s_addc_u32 s61, s53, 0
	s_add_i32 s6, s6, s4
	global_load_lds_dwordx4 v[130:131], off
	v_lshl_add_u64 v[130:131], s[60:61], 0, v[140:141]
	s_mov_b32 m0, s6
	s_add_i32 s7, s6, 0x2000
	global_load_lds_dwordx4 v[130:131], off
	v_lshl_add_u64 v[130:131], s[60:61], 0, v[144:145]
	s_mov_b32 m0, s7
	v_lshl_add_u64 v[180:181], s[48:49], 0, v[138:139]
	global_load_lds_dwordx4 v[130:131], off
	v_lshl_add_u64 v[130:131], v[180:181], 0, vcc
	s_mov_b32 m0, s18
	v_lshl_add_u64 v[194:195], s[48:49], 0, v[142:143]
	global_load_lds_dwordx4 v[130:131], off
	v_lshl_add_u64 v[130:131], v[194:195], 0, vcc
	s_mov_b32 m0, s19
	s_nop 0
	global_load_lds_dwordx4 v[130:131], off
	s_setprio 1
	s_waitcnt vmcnt(8)
	s_waitcnt lgkmcnt(0)
	s_barrier
	v_mfma_f32_16x16x32_bf16 v[130:133], v[0:3], v[60:63], 0
	v_mfma_f32_16x16x32_bf16 v[150:153], v[0:3], v[106:109], 0
	v_mfma_f32_16x16x32_bf16 v[158:161], v[0:3], v[114:117], 0
	v_mfma_f32_16x16x32_bf16 v[0:3], v[0:3], v[122:125], 0
	v_mfma_f32_16x16x32_bf16 v[130:133], v[4:7], v[102:105], v[130:133]
	v_mfma_f32_16x16x32_bf16 v[134:137], v[8:11], v[60:63], 0
	v_mfma_f32_16x16x32_bf16 v[150:153], v[4:7], v[110:113], v[150:153]
	v_mfma_f32_16x16x32_bf16 v[158:161], v[4:7], v[118:121], v[158:161]
	v_mfma_f32_16x16x32_bf16 v[0:3], v[4:7], v[126:129], v[0:3]
	v_mfma_f32_16x16x32_bf16 v[4:7], v[8:11], v[122:125], 0
	v_mfma_f32_16x16x32_bf16 v[134:137], v[12:15], v[102:105], v[134:137]
	v_mfma_f32_16x16x32_bf16 v[154:157], v[8:11], v[106:109], 0
	v_mfma_f32_16x16x32_bf16 v[162:165], v[8:11], v[114:117], 0
	v_mfma_f32_16x16x32_bf16 v[4:7], v[12:15], v[126:129], v[4:7]
	v_mfma_f32_16x16x32_bf16 v[154:157], v[12:15], v[110:113], v[154:157]
	v_mfma_f32_16x16x32_bf16 v[162:165], v[12:15], v[118:121], v[162:165]
	s_setprio 0
	s_setprio 1
	v_mfma_f32_16x16x32_bf16 v[8:11], v[16:19], v[60:63], 0
	v_mfma_f32_16x16x32_bf16 v[12:15], v[24:27], v[60:63], 0
	v_mfma_f32_16x16x32_bf16 v[8:11], v[20:23], v[102:105], v[8:11]
	v_mfma_f32_16x16x32_bf16 v[12:15], v[28:31], v[102:105], v[12:15]
	v_mfma_f32_16x16x32_bf16 v[60:63], v[16:19], v[106:109], 0
	v_mfma_f32_16x16x32_bf16 v[102:105], v[24:27], v[106:109], 0
	v_mfma_f32_16x16x32_bf16 v[106:109], v[16:19], v[114:117], 0
	v_mfma_f32_16x16x32_bf16 v[16:19], v[16:19], v[122:125], 0
	v_mfma_f32_16x16x32_bf16 v[60:63], v[20:23], v[110:113], v[60:63]
	v_mfma_f32_16x16x32_bf16 v[106:109], v[20:23], v[118:121], v[106:109]
	v_mfma_f32_16x16x32_bf16 v[16:19], v[20:23], v[126:129], v[16:19]
	v_mfma_f32_16x16x32_bf16 v[20:23], v[24:27], v[122:125], 0
	v_mfma_f32_16x16x32_bf16 v[102:105], v[28:31], v[110:113], v[102:105]
	v_mfma_f32_16x16x32_bf16 v[110:113], v[24:27], v[114:117], 0
	v_mfma_f32_16x16x32_bf16 v[20:23], v[28:31], v[126:129], v[20:23]
	v_mfma_f32_16x16x32_bf16 v[110:113], v[28:31], v[118:121], v[110:113]
	s_setprio 0
	s_barrier
	s_add_i32 s57, 0, 0x18000
	s_add_i32 s62, 0, 0x1c000
	v_add_u32_e32 v204, s57, v148
	v_add_u32_e32 v205, s62, v148
	ds_read_b128 v[24:27], v204
	ds_read_b128 v[28:31], v204 offset:1024
	ds_read_b128 v[114:117], v204 offset:2048
	ds_read_b128 v[118:121], v204 offset:3072
	ds_read_b128 v[122:125], v205
	ds_read_b128 v[126:129], v205 offset:1024
	ds_read_b128 v[166:169], v205 offset:2048
	ds_read_b128 v[170:173], v205 offset:3072
	s_add_u32 s60, s48, 0x10100
	s_addc_u32 s61, s49, 0
	s_mov_b32 m0, s20
	v_lshl_add_u64 v[202:203], s[60:61], 0, v[138:139]
	ds_read_b128 v[174:177], v149 offset:32768
	ds_read_b128 v[182:185], v149 offset:33792
	ds_read_b128 v[186:189], v149 offset:34816
	ds_read_b128 v[190:193], v149 offset:35840
	ds_read_b128 v[214:217], v149 offset:36864
	ds_read_b128 v[218:221], v149 offset:37888
	ds_read_b128 v[222:225], v149 offset:38912
	ds_read_b128 v[226:229], v149 offset:39936
	global_load_lds_dwordx4 v[202:203], off
	v_lshl_add_u64 v[202:203], s[60:61], 0, v[142:143]
	s_mov_b32 m0, s36
	s_nop 0
	global_load_lds_dwordx4 v[202:203], off
	s_setprio 1
	s_waitcnt vmcnt(8)
	s_waitcnt lgkmcnt(0)
	s_barrier
	v_mfma_f32_16x16x32_bf16 v[64:67], v[24:27], v[174:177], v[64:67]
	v_mfma_f32_16x16x32_bf16 v[68:71], v[114:117], v[174:177], v[68:71]
	v_mfma_f32_16x16x32_bf16 v[72:75], v[24:27], v[186:189], v[72:75]
	v_mfma_f32_16x16x32_bf16 v[76:79], v[114:117], v[186:189], v[76:79]
	v_mfma_f32_16x16x32_bf16 v[80:83], v[24:27], v[214:217], v[80:83]
	v_mfma_f32_16x16x32_bf16 v[84:87], v[114:117], v[214:217], v[84:87]
	v_mfma_f32_16x16x32_bf16 v[88:91], v[24:27], v[222:225], v[88:91]
	v_mfma_f32_16x16x32_bf16 v[92:95], v[114:117], v[222:225], v[92:95]
	v_mfma_f32_16x16x32_bf16 v[64:67], v[28:31], v[182:185], v[64:67]
	v_mfma_f32_16x16x32_bf16 v[68:71], v[118:121], v[182:185], v[68:71]
	v_mfma_f32_16x16x32_bf16 v[72:75], v[28:31], v[190:193], v[72:75]
	v_mfma_f32_16x16x32_bf16 v[76:79], v[118:121], v[190:193], v[76:79]
	v_mfma_f32_16x16x32_bf16 v[80:83], v[28:31], v[218:221], v[80:83]
	v_mfma_f32_16x16x32_bf16 v[84:87], v[118:121], v[218:221], v[84:87]
	v_mfma_f32_16x16x32_bf16 v[88:91], v[28:31], v[226:229], v[88:91]
	v_mfma_f32_16x16x32_bf16 v[92:95], v[118:121], v[226:229], v[92:95]
	s_setprio 0
	s_setprio 1
	v_mfma_f32_16x16x32_bf16 v[98:101], v[122:125], v[174:177], v[98:101]
	v_mfma_f32_16x16x32_bf16 v[32:35], v[166:169], v[174:177], v[32:35]
	v_mfma_f32_16x16x32_bf16 v[36:39], v[122:125], v[186:189], v[36:39]
	v_mfma_f32_16x16x32_bf16 v[40:43], v[166:169], v[186:189], v[40:43]
	v_mfma_f32_16x16x32_bf16 v[44:47], v[122:125], v[214:217], v[44:47]
	v_mfma_f32_16x16x32_bf16 v[48:51], v[166:169], v[214:217], v[48:51]
	v_mfma_f32_16x16x32_bf16 v[52:55], v[122:125], v[222:225], v[52:55]
	v_mfma_f32_16x16x32_bf16 v[56:59], v[166:169], v[222:225], v[56:59]
	v_mfma_f32_16x16x32_bf16 v[98:101], v[126:129], v[182:185], v[98:101]
	v_mfma_f32_16x16x32_bf16 v[32:35], v[170:173], v[182:185], v[32:35]
	v_mfma_f32_16x16x32_bf16 v[36:39], v[126:129], v[190:193], v[36:39]
	v_mfma_f32_16x16x32_bf16 v[40:43], v[170:173], v[190:193], v[40:43]
	v_mfma_f32_16x16x32_bf16 v[44:47], v[126:129], v[218:221], v[44:47]
	v_mfma_f32_16x16x32_bf16 v[48:51], v[170:173], v[218:221], v[48:51]
	v_mfma_f32_16x16x32_bf16 v[52:55], v[126:129], v[226:229], v[52:55]
	v_mfma_f32_16x16x32_bf16 v[56:59], v[170:173], v[226:229], v[56:59]
	s_setprio 0
	s_barrier
	s_add_i32 s57, s57, s4
	s_mov_b64 vcc, 0x180
	s_add_i32 s35, s57, 0x2000
	v_lshl_add_u64 v[146:147], v[146:147], 0, vcc
	s_mov_b32 m0, s57
	s_add_u32 s60, s52, 0x10180
	ds_read_b128 v[174:177], v149 offset:49152
	ds_read_b128 v[182:185], v149 offset:50176
	ds_read_b128 v[186:189], v149 offset:51200
	ds_read_b128 v[190:193], v149 offset:52224
	ds_read_b128 v[214:217], v149 offset:53248
	ds_read_b128 v[218:221], v149 offset:54272
	ds_read_b128 v[222:225], v149 offset:55296
	ds_read_b128 v[226:229], v149 offset:56320
	global_load_lds_dwordx4 v[146:147], off
	v_lshl_add_u64 v[146:147], v[178:179], 0, vcc
	s_mov_b32 m0, s35
	s_addc_u32 s61, s53, 0
	s_add_i32 s52, s62, s4
	global_load_lds_dwordx4 v[146:147], off
	v_lshl_add_u64 v[146:147], s[60:61], 0, v[140:141]
	s_mov_b32 m0, s52
	s_add_i32 s53, s52, 0x2000
	global_load_lds_dwordx4 v[146:147], off
	v_lshl_add_u64 v[146:147], s[60:61], 0, v[144:145]
	s_mov_b32 m0, s53
	s_nop 0
	global_load_lds_dwordx4 v[146:147], off
	v_lshl_add_u64 v[146:147], v[180:181], 0, vcc
	s_mov_b32 m0, s45
	s_nop 0
	global_load_lds_dwordx4 v[146:147], off
	v_lshl_add_u64 v[146:147], v[194:195], 0, vcc
	s_mov_b32 m0, s47
	s_nop 0
	global_load_lds_dwordx4 v[146:147], off
	s_setprio 1
	s_waitcnt vmcnt(8)
	s_waitcnt lgkmcnt(0)
	s_barrier
	v_mfma_f32_16x16x32_bf16 v[130:133], v[24:27], v[174:177], v[130:133]
	v_mfma_f32_16x16x32_bf16 v[134:137], v[114:117], v[174:177], v[134:137]
	v_mfma_f32_16x16x32_bf16 v[0:3], v[24:27], v[222:225], v[0:3]
	v_mfma_f32_16x16x32_bf16 v[4:7], v[114:117], v[222:225], v[4:7]
	v_mfma_f32_16x16x32_bf16 v[130:133], v[28:31], v[182:185], v[130:133]
	v_mfma_f32_16x16x32_bf16 v[134:137], v[118:121], v[182:185], v[134:137]
	v_mfma_f32_16x16x32_bf16 v[150:153], v[24:27], v[186:189], v[150:153]
	v_mfma_f32_16x16x32_bf16 v[154:157], v[114:117], v[186:189], v[154:157]
	v_mfma_f32_16x16x32_bf16 v[158:161], v[24:27], v[214:217], v[158:161]
	v_mfma_f32_16x16x32_bf16 v[162:165], v[114:117], v[214:217], v[162:165]
	v_mfma_f32_16x16x32_bf16 v[0:3], v[28:31], v[226:229], v[0:3]
	v_mfma_f32_16x16x32_bf16 v[4:7], v[118:121], v[226:229], v[4:7]
	v_mfma_f32_16x16x32_bf16 v[150:153], v[28:31], v[190:193], v[150:153]
	v_mfma_f32_16x16x32_bf16 v[154:157], v[118:121], v[190:193], v[154:157]
	v_mfma_f32_16x16x32_bf16 v[158:161], v[28:31], v[218:221], v[158:161]
	v_mfma_f32_16x16x32_bf16 v[162:165], v[118:121], v[218:221], v[162:165]
	s_setprio 0
	s_setprio 1
	v_mfma_f32_16x16x32_bf16 v[8:11], v[122:125], v[174:177], v[8:11]
	v_mfma_f32_16x16x32_bf16 v[12:15], v[166:169], v[174:177], v[12:15]
	v_mfma_f32_16x16x32_bf16 v[24:27], v[122:125], v[186:189], v[60:63]
	v_mfma_f32_16x16x32_bf16 v[28:31], v[166:169], v[186:189], v[102:105]
	v_mfma_f32_16x16x32_bf16 v[60:63], v[122:125], v[214:217], v[106:109]
	v_mfma_f32_16x16x32_bf16 v[102:105], v[166:169], v[214:217], v[110:113]
	v_mfma_f32_16x16x32_bf16 v[16:19], v[122:125], v[222:225], v[16:19]
	v_mfma_f32_16x16x32_bf16 v[20:23], v[166:169], v[222:225], v[20:23]
	v_mfma_f32_16x16x32_bf16 v[8:11], v[126:129], v[182:185], v[8:11]
	v_mfma_f32_16x16x32_bf16 v[12:15], v[170:173], v[182:185], v[12:15]
	v_mfma_f32_16x16x32_bf16 v[24:27], v[126:129], v[190:193], v[24:27]
	v_mfma_f32_16x16x32_bf16 v[28:31], v[170:173], v[190:193], v[28:31]
	v_mfma_f32_16x16x32_bf16 v[60:63], v[126:129], v[218:221], v[60:63]
	v_mfma_f32_16x16x32_bf16 v[102:105], v[170:173], v[218:221], v[102:105]
	v_mfma_f32_16x16x32_bf16 v[16:19], v[126:129], v[226:229], v[16:19]
	v_mfma_f32_16x16x32_bf16 v[20:23], v[170:173], v[226:229], v[20:23]
	s_setprio 0
	s_barrier
	ds_read_b128 v[106:109], v96
	ds_read_b128 v[110:113], v96 offset:1024
	ds_read_b128 v[114:117], v96 offset:2048
	ds_read_b128 v[118:121], v96 offset:3072
	ds_read_b128 v[122:125], v198
	ds_read_b128 v[126:129], v198 offset:1024
	ds_read_b128 v[166:169], v198 offset:2048
	ds_read_b128 v[170:173], v198 offset:3072
	s_add_u32 s48, s48, 0x10180
	s_addc_u32 s49, s49, 0
	s_mov_b32 m0, s56
	v_lshl_add_u64 v[146:147], s[48:49], 0, v[138:139]
	ds_read_b128 v[174:177], v149
	ds_read_b128 v[182:185], v149 offset:1024
	ds_read_b128 v[186:189], v149 offset:2048
	ds_read_b128 v[190:193], v149 offset:3072
	ds_read_b128 v[214:217], v149 offset:4096
	ds_read_b128 v[218:221], v149 offset:5120
	ds_read_b128 v[222:225], v149 offset:6144
	ds_read_b128 v[226:229], v149 offset:7168
	global_load_lds_dwordx4 v[146:147], off
	v_lshl_add_u64 v[146:147], s[48:49], 0, v[142:143]
	s_mov_b32 m0, s2
	s_nop 0
	global_load_lds_dwordx4 v[146:147], off
	s_setprio 1
	s_waitcnt vmcnt(8)
	s_waitcnt lgkmcnt(0)
	s_barrier
	v_mfma_f32_16x16x32_bf16 v[64:67], v[106:109], v[174:177], v[64:67]
	v_mfma_f32_16x16x32_bf16 v[68:71], v[114:117], v[174:177], v[68:71]
	v_mfma_f32_16x16x32_bf16 v[72:75], v[106:109], v[186:189], v[72:75]
	v_mfma_f32_16x16x32_bf16 v[76:79], v[114:117], v[186:189], v[76:79]
	v_mfma_f32_16x16x32_bf16 v[80:83], v[106:109], v[214:217], v[80:83]
	v_mfma_f32_16x16x32_bf16 v[84:87], v[114:117], v[214:217], v[84:87]
	v_mfma_f32_16x16x32_bf16 v[88:91], v[106:109], v[222:225], v[88:91]
	v_mfma_f32_16x16x32_bf16 v[92:95], v[114:117], v[222:225], v[92:95]
	v_mfma_f32_16x16x32_bf16 v[64:67], v[110:113], v[182:185], v[64:67]
	v_mfma_f32_16x16x32_bf16 v[68:71], v[118:121], v[182:185], v[68:71]
	v_mfma_f32_16x16x32_bf16 v[72:75], v[110:113], v[190:193], v[72:75]
	v_mfma_f32_16x16x32_bf16 v[76:79], v[118:121], v[190:193], v[76:79]
	v_mfma_f32_16x16x32_bf16 v[80:83], v[110:113], v[218:221], v[80:83]
	v_mfma_f32_16x16x32_bf16 v[84:87], v[118:121], v[218:221], v[84:87]
	v_mfma_f32_16x16x32_bf16 v[88:91], v[110:113], v[226:229], v[88:91]
	v_mfma_f32_16x16x32_bf16 v[92:95], v[118:121], v[226:229], v[92:95]
	s_setprio 0
	s_setprio 1
	v_mfma_f32_16x16x32_bf16 v[32:35], v[166:169], v[174:177], v[32:35]
	v_mfma_f32_16x16x32_bf16 v[36:39], v[122:125], v[186:189], v[36:39]
	v_mfma_f32_16x16x32_bf16 v[40:43], v[166:169], v[186:189], v[40:43]
	v_mfma_f32_16x16x32_bf16 v[44:47], v[122:125], v[214:217], v[44:47]
	v_mfma_f32_16x16x32_bf16 v[48:51], v[166:169], v[214:217], v[48:51]
	v_mfma_f32_16x16x32_bf16 v[52:55], v[122:125], v[222:225], v[52:55]
	v_mfma_f32_16x16x32_bf16 v[56:59], v[166:169], v[222:225], v[56:59]
	v_mfma_f32_16x16x32_bf16 v[98:101], v[122:125], v[174:177], v[98:101]
	v_mfma_f32_16x16x32_bf16 v[32:35], v[170:173], v[182:185], v[32:35]
	v_mfma_f32_16x16x32_bf16 v[36:39], v[126:129], v[190:193], v[36:39]
	v_mfma_f32_16x16x32_bf16 v[40:43], v[170:173], v[190:193], v[40:43]
	v_mfma_f32_16x16x32_bf16 v[44:47], v[126:129], v[218:221], v[44:47]
	v_mfma_f32_16x16x32_bf16 v[48:51], v[170:173], v[218:221], v[48:51]
	v_mfma_f32_16x16x32_bf16 v[52:55], v[126:129], v[226:229], v[52:55]
	v_mfma_f32_16x16x32_bf16 v[56:59], v[170:173], v[226:229], v[56:59]
	v_mfma_f32_16x16x32_bf16 v[230:233], v[126:129], v[182:185], v[98:101]
	s_setprio 0
	s_barrier
	s_mov_b32 m0, s25
	v_lshl_add_u64 v[146:147], s[50:51], 0, v[140:141]
	s_add_u32 s2, s50, 0x10000
	ds_read_b128 v[98:101], v149 offset:16384
	ds_read_b128 v[174:177], v149 offset:17408
	ds_read_b128 v[182:185], v149 offset:18432
	ds_read_b128 v[186:189], v149 offset:19456
	ds_read_b128 v[190:193], v149 offset:20480
	ds_read_b128 v[214:217], v149 offset:21504
	ds_read_b128 v[218:221], v149 offset:22528
	ds_read_b128 v[222:225], v149 offset:23552
	global_load_lds_dwordx4 v[146:147], off
	v_lshl_add_u64 v[194:195], s[50:51], 0, v[144:145]
	s_mov_b32 m0, s3
	s_addc_u32 s3, s51, 0
	global_load_lds_dwordx4 v[194:195], off
	v_lshl_add_u64 v[178:179], s[2:3], 0, v[140:141]
	s_mov_b32 m0, s6
	v_lshl_add_u64 v[198:199], s[58:59], 0, v[138:139]
	global_load_lds_dwordx4 v[178:179], off
	v_lshl_add_u64 v[178:179], s[2:3], 0, v[144:145]
	s_mov_b32 m0, s7
	v_lshl_add_u64 v[200:201], s[58:59], 0, v[142:143]
	global_load_lds_dwordx4 v[178:179], off
	s_mov_b32 m0, s18
	s_nop 0
	global_load_lds_dwordx4 v[198:199], off
	s_mov_b32 m0, s19
	s_nop 0
	global_load_lds_dwordx4 v[200:201], off
	s_setprio 1
	s_waitcnt vmcnt(8)
	s_waitcnt lgkmcnt(0)
	s_barrier
	v_mfma_f32_16x16x32_bf16 v[130:133], v[106:109], v[98:101], v[130:133]
	v_mfma_f32_16x16x32_bf16 v[226:229], v[110:113], v[174:177], v[130:133]
	v_mfma_f32_16x16x32_bf16 v[130:133], v[114:117], v[98:101], v[134:137]
	v_mfma_f32_16x16x32_bf16 v[234:237], v[118:121], v[174:177], v[130:133]
	v_mfma_f32_16x16x32_bf16 v[130:133], v[106:109], v[182:185], v[150:153]
	v_mfma_f32_16x16x32_bf16 v[150:153], v[110:113], v[186:189], v[130:133]
	v_mfma_f32_16x16x32_bf16 v[130:133], v[114:117], v[182:185], v[154:157]
	v_mfma_f32_16x16x32_bf16 v[154:157], v[118:121], v[186:189], v[130:133]
	v_mfma_f32_16x16x32_bf16 v[130:133], v[106:109], v[190:193], v[158:161]
	v_mfma_f32_16x16x32_bf16 v[0:3], v[106:109], v[218:221], v[0:3]
	v_mfma_f32_16x16x32_bf16 v[4:7], v[114:117], v[218:221], v[4:7]
	v_mfma_f32_16x16x32_bf16 v[158:161], v[110:113], v[214:217], v[130:133]
	v_mfma_f32_16x16x32_bf16 v[130:133], v[114:117], v[190:193], v[162:165]
	v_mfma_f32_16x16x32_bf16 v[0:3], v[110:113], v[222:225], v[0:3]
	v_mfma_f32_16x16x32_bf16 v[4:7], v[118:121], v[222:225], v[4:7]
	v_mfma_f32_16x16x32_bf16 v[162:165], v[118:121], v[214:217], v[130:133]
	s_setprio 0
	s_setprio 1
	v_mfma_f32_16x16x32_bf16 v[8:11], v[122:125], v[98:101], v[8:11]
	v_mfma_f32_16x16x32_bf16 v[12:15], v[166:169], v[98:101], v[12:15]
	v_mfma_f32_16x16x32_bf16 v[24:27], v[122:125], v[182:185], v[24:27]
	v_mfma_f32_16x16x32_bf16 v[28:31], v[166:169], v[182:185], v[28:31]
	v_mfma_f32_16x16x32_bf16 v[60:63], v[122:125], v[190:193], v[60:63]
	v_mfma_f32_16x16x32_bf16 v[16:19], v[122:125], v[218:221], v[16:19]
	v_mfma_f32_16x16x32_bf16 v[8:11], v[126:129], v[174:177], v[8:11]
	v_mfma_f32_16x16x32_bf16 v[12:15], v[170:173], v[174:177], v[12:15]
	v_mfma_f32_16x16x32_bf16 v[24:27], v[126:129], v[186:189], v[24:27]
	v_mfma_f32_16x16x32_bf16 v[28:31], v[170:173], v[186:189], v[28:31]
	v_mfma_f32_16x16x32_bf16 v[106:109], v[126:129], v[214:217], v[60:63]
	v_mfma_f32_16x16x32_bf16 v[60:63], v[166:169], v[190:193], v[102:105]
	v_mfma_f32_16x16x32_bf16 v[174:177], v[126:129], v[222:225], v[16:19]
	v_mfma_f32_16x16x32_bf16 v[16:19], v[166:169], v[218:221], v[20:23]
	v_mfma_f32_16x16x32_bf16 v[110:113], v[170:173], v[214:217], v[60:63]
	v_mfma_f32_16x16x32_bf16 v[166:169], v[170:173], v[222:225], v[16:19]
	s_setprio 0
	s_barrier
	s_nop 3
	ds_read_b128 v[16:19], v204
	ds_read_b128 v[20:23], v204 offset:1024
	ds_read_b128 v[170:173], v204 offset:2048
	ds_read_b128 v[182:185], v204 offset:3072
	ds_read_b128 v[186:189], v205
	ds_read_b128 v[190:193], v205 offset:1024
	ds_read_b128 v[214:217], v205 offset:2048
	ds_read_b128 v[218:221], v205 offset:3072
	s_add_u32 s2, s58, 0x10000
	s_addc_u32 s3, s59, 0
	s_mov_b32 m0, s20
	v_lshl_add_u64 v[98:99], s[2:3], 0, v[138:139]
	ds_read_b128 v[60:63], v149 offset:32768
	ds_read_b128 v[222:225], v149 offset:33792
	ds_read_b128 v[238:241], v149 offset:34816
	ds_read_b128 v[242:245], v149 offset:35840
	ds_read_b128 v[246:249], v149 offset:36864
	ds_read_b128 v[202:205], v149 offset:37888
	ds_read_b128 v[178:181], v149 offset:38912
	ds_read_b128 v[206:209], v149 offset:39936
	global_load_lds_dwordx4 v[98:99], off
	v_lshl_add_u64 v[98:99], s[2:3], 0, v[142:143]
	s_mov_b32 m0, s36
	s_nop 0
	global_load_lds_dwordx4 v[98:99], off
	s_setprio 1
	s_waitcnt vmcnt(8)
	s_waitcnt lgkmcnt(0)
	s_barrier
	v_mfma_f32_16x16x32_bf16 v[64:67], v[16:19], v[60:63], v[64:67]
	v_mfma_f32_16x16x32_bf16 v[134:137], v[20:23], v[222:225], v[64:67]
	v_mfma_f32_16x16x32_bf16 v[64:67], v[170:173], v[60:63], v[68:71]
	v_mfma_f32_16x16x32_bf16 v[130:133], v[182:185], v[222:225], v[64:67]
	v_mfma_f32_16x16x32_bf16 v[64:67], v[16:19], v[238:241], v[72:75]
	v_mfma_f32_16x16x32_bf16 v[126:129], v[20:23], v[242:245], v[64:67]
	v_mfma_f32_16x16x32_bf16 v[64:67], v[170:173], v[238:241], v[76:79]
	v_mfma_f32_16x16x32_bf16 v[122:125], v[182:185], v[242:245], v[64:67]
	v_mfma_f32_16x16x32_bf16 v[64:67], v[16:19], v[246:249], v[80:83]
	v_mfma_f32_16x16x32_bf16 v[118:121], v[20:23], v[202:205], v[64:67]
	v_mfma_f32_16x16x32_bf16 v[64:67], v[170:173], v[246:249], v[84:87]
	v_mfma_f32_16x16x32_bf16 v[114:117], v[182:185], v[202:205], v[64:67]
	v_mfma_f32_16x16x32_bf16 v[64:67], v[16:19], v[178:181], v[88:91]
	v_mfma_f32_16x16x32_bf16 v[102:105], v[20:23], v[206:209], v[64:67]
	v_mfma_f32_16x16x32_bf16 v[64:67], v[170:173], v[178:181], v[92:95]
	v_mfma_f32_16x16x32_bf16 v[98:101], v[182:185], v[206:209], v[64:67]
	s_setprio 0
	s_setprio 1
	v_mfma_f32_16x16x32_bf16 v[64:67], v[186:189], v[60:63], v[230:233]
	v_mfma_f32_16x16x32_bf16 v[32:35], v[214:217], v[60:63], v[32:35]
	v_mfma_f32_16x16x32_bf16 v[68:71], v[190:193], v[222:225], v[64:67]
	v_mfma_f32_16x16x32_bf16 v[64:67], v[218:221], v[222:225], v[32:35]
	v_mfma_f32_16x16x32_bf16 v[32:35], v[186:189], v[238:241], v[36:39]
	v_mfma_f32_16x16x32_bf16 v[80:83], v[190:193], v[242:245], v[32:35]
	v_mfma_f32_16x16x32_bf16 v[32:35], v[214:217], v[238:241], v[40:43]
	v_mfma_f32_16x16x32_bf16 v[72:75], v[218:221], v[242:245], v[32:35]
	v_mfma_f32_16x16x32_bf16 v[32:35], v[186:189], v[246:249], v[44:47]
	v_mfma_f32_16x16x32_bf16 v[84:87], v[190:193], v[202:205], v[32:35]
	v_mfma_f32_16x16x32_bf16 v[32:35], v[214:217], v[246:249], v[48:51]
	v_mfma_f32_16x16x32_bf16 v[76:79], v[218:221], v[202:205], v[32:35]
	v_mfma_f32_16x16x32_bf16 v[32:35], v[186:189], v[178:181], v[52:55]
	v_mfma_f32_16x16x32_bf16 v[92:95], v[190:193], v[206:209], v[32:35]
	v_mfma_f32_16x16x32_bf16 v[32:35], v[214:217], v[178:181], v[56:59]
	v_mfma_f32_16x16x32_bf16 v[88:91], v[218:221], v[206:209], v[32:35]
	s_setprio 0
	s_barrier
	s_mov_b32 m0, s57
	s_nop 3
	v_lshl_add_u64 v[32:33], v[146:147], 0, s[30:31]
	s_add_u32 s2, s50, 0x10080
	ds_read_b128 v[178:181], v149 offset:49152
	ds_read_b128 v[202:205], v149 offset:50176
	ds_read_b128 v[206:209], v149 offset:51200
	ds_read_b128 v[222:225], v149 offset:52224
	ds_read_b128 v[230:233], v149 offset:53248
	ds_read_b128 v[238:241], v149 offset:54272
	ds_read_b128 v[242:245], v149 offset:55296
	ds_read_b128 v[246:249], v149 offset:56320
	global_load_lds_dwordx4 v[32:33], off
	v_lshl_add_u64 v[32:33], v[194:195], 0, s[30:31]
	s_mov_b32 m0, s35
	s_addc_u32 s3, s51, 0
	global_load_lds_dwordx4 v[32:33], off
	v_lshl_add_u64 v[32:33], s[2:3], 0, v[140:141]
	s_mov_b32 m0, s52
	s_nop 0
	global_load_lds_dwordx4 v[32:33], off
	v_lshl_add_u64 v[32:33], s[2:3], 0, v[144:145]
	s_mov_b32 m0, s53
	s_nop 0
	global_load_lds_dwordx4 v[32:33], off
	v_lshl_add_u64 v[32:33], v[198:199], 0, s[30:31]
	s_mov_b32 m0, s45
	s_nop 0
	global_load_lds_dwordx4 v[32:33], off
	v_lshl_add_u64 v[32:33], v[200:201], 0, s[30:31]
	s_mov_b32 m0, s47
	s_nop 0
	global_load_lds_dwordx4 v[32:33], off
	s_setprio 1
	s_waitcnt vmcnt(8)
	s_waitcnt lgkmcnt(0)
	s_barrier
	v_mfma_f32_16x16x32_bf16 v[32:35], v[16:19], v[178:181], v[226:229]
	v_mfma_f32_16x16x32_bf16 v[60:63], v[20:23], v[202:205], v[32:35]
	v_mfma_f32_16x16x32_bf16 v[32:35], v[170:173], v[178:181], v[234:237]
	v_mfma_f32_16x16x32_bf16 v[56:59], v[182:185], v[202:205], v[32:35]
	v_mfma_f32_16x16x32_bf16 v[32:35], v[16:19], v[206:209], v[150:153]
	v_mfma_f32_16x16x32_bf16 v[52:55], v[20:23], v[222:225], v[32:35]
	v_mfma_f32_16x16x32_bf16 v[32:35], v[170:173], v[206:209], v[154:157]
	v_mfma_f32_16x16x32_bf16 v[48:51], v[182:185], v[222:225], v[32:35]
	v_mfma_f32_16x16x32_bf16 v[32:35], v[16:19], v[230:233], v[158:161]
	v_mfma_f32_16x16x32_bf16 v[0:3], v[16:19], v[242:245], v[0:3]
	v_mfma_f32_16x16x32_bf16 v[44:47], v[20:23], v[238:241], v[32:35]
	v_mfma_f32_16x16x32_bf16 v[32:35], v[170:173], v[230:233], v[162:165]
	v_mfma_f32_16x16x32_bf16 v[36:39], v[20:23], v[246:249], v[0:3]
	v_mfma_f32_16x16x32_bf16 v[0:3], v[170:173], v[242:245], v[4:7]
	v_mfma_f32_16x16x32_bf16 v[40:43], v[182:185], v[238:241], v[32:35]
	v_mfma_f32_16x16x32_bf16 v[32:35], v[182:185], v[246:249], v[0:3]
	s_setprio 0
	s_setprio 1
	v_mfma_f32_16x16x32_bf16 v[0:3], v[186:189], v[178:181], v[8:11]
	v_mfma_f32_16x16x32_bf16 v[4:7], v[190:193], v[202:205], v[0:3]
	v_mfma_f32_16x16x32_bf16 v[0:3], v[214:217], v[178:181], v[12:15]
	v_mfma_f32_16x16x32_bf16 v[8:11], v[186:189], v[206:209], v[24:27]
	v_mfma_f32_16x16x32_bf16 v[12:15], v[186:189], v[230:233], v[106:109]
	v_mfma_f32_16x16x32_bf16 v[24:27], v[186:189], v[242:245], v[174:177]
	v_mfma_f32_16x16x32_bf16 v[16:19], v[190:193], v[222:225], v[8:11]
	v_mfma_f32_16x16x32_bf16 v[8:11], v[214:217], v[206:209], v[28:31]
	v_mfma_f32_16x16x32_bf16 v[20:23], v[190:193], v[238:241], v[12:15]
	v_mfma_f32_16x16x32_bf16 v[12:15], v[214:217], v[230:233], v[110:113]
	v_mfma_f32_16x16x32_bf16 v[28:31], v[190:193], v[246:249], v[24:27]
	v_mfma_f32_16x16x32_bf16 v[24:27], v[214:217], v[242:245], v[166:169]
	v_mfma_f32_16x16x32_bf16 v[0:3], v[218:221], v[202:205], v[0:3]
	v_mfma_f32_16x16x32_bf16 v[8:11], v[218:221], v[222:225], v[8:11]
	v_mfma_f32_16x16x32_bf16 v[12:15], v[218:221], v[238:241], v[12:15]
	v_mfma_f32_16x16x32_bf16 v[24:27], v[218:221], v[246:249], v[24:27]
	s_setprio 0
	s_barrier
	s_nop 0
	s_nop 0
	s_nop 0
	s_nop 0
	s_nop 0
	s_nop 0
	s_nop 0
	s_nop 0
	s_andn2_b64 vcc, exec, s[14:15]
	s_cbranch_vccnz .LBB0_682
	s_barrier

.LBB0_973:
	s_add_u32 s6, s34, s2
	s_addc_u32 s13, s35, 0
	s_add_u32 s3, s6, 0x100
	s_addc_u32 s23, s13, 0
	s_and_b64 s[36:37], s[60:61], exec
	s_cselect_b32 s73, s43, s23
	s_cselect_b32 s72, s42, s3
	s_add_u32 s2, s24, s2
	s_addc_u32 s3, s25, 0
	s_add_u32 s23, s2, 0x100
	s_addc_u32 s36, s3, 0
	s_add_i32 s47, 0, 0x10000
	s_and_b64 s[2:3], s[60:61], exec
	s_cselect_b32 s75, s53, s36
	s_cselect_b32 s74, s52, s23
	s_add_i32 s49, 0, 0x14000
	s_add_u32 s86, s6, 0x80080
	s_addc_u32 s87, s13, 0
	s_add_i32 s40, s47, s4
	s_add_i32 m0, s5, 0xc000
	s_add_i32 s51, s5, 0xe000
	s_add_i32 s23, s40, 0x2000
	s_add_u32 s82, s74, 0x80000
	v_add_u32_e32 v148, s47, v132
	v_add_u32_e32 v164, s49, v132
	s_addc_u32 s83, s75, 0
	s_add_i32 s37, s49, s4
	ds_read_b128 v[136:139], v148
	ds_read_b128 v[140:143], v148 offset:1024
	ds_read_b128 v[144:147], v148 offset:2048
	ds_read_b128 v[148:151], v148 offset:3072
	ds_read_b128 v[152:155], v164
	ds_read_b128 v[156:159], v164 offset:1024
	ds_read_b128 v[160:163], v164 offset:2048
	ds_read_b128 v[164:167], v164 offset:3072
	s_add_i32 s36, s37, 0x2000
	s_add_i32 s13, 0, 0x18000
	s_add_i32 s6, 0, 0x1c000
	s_add_u32 s62, s72, 0x80000
	s_addc_u32 s63, s73, 0
	s_add_i32 s3, s13, s4
	s_add_i32 s2, s3, 0x2000
	s_add_u32 s60, s74, 0x80080
	s_addc_u32 s61, s75, 0
	s_add_i32 s49, s6, s4
	s_add_i32 s47, s49, 0x2000
	v_lshl_add_u64 v[198:199], s[86:87], 0, v[96:97]
	ds_read_b128 v[168:171], v135
	ds_read_b128 v[172:175], v135 offset:1024
	ds_read_b128 v[176:179], v135 offset:2048
	ds_read_b128 v[180:183], v135 offset:3072
	ds_read_b128 v[184:187], v135 offset:4096
	ds_read_b128 v[188:191], v135 offset:5120
	ds_read_b128 v[192:195], v135 offset:6144
	ds_read_b128 v[202:205], v135 offset:7168
	global_load_lds_dwordx4 v[198:199], off
	v_lshl_add_u64 v[198:199], s[86:87], 0, v[130:131]
	s_mov_b32 m0, s51
	s_nop 0
	global_load_lds_dwordx4 v[198:199], off
	s_setprio 1
	s_waitcnt vmcnt(8)
	s_waitcnt lgkmcnt(0)
	s_barrier
	v_mfma_f32_16x16x32_bf16 v[126:129], v[136:139], v[168:171], v[126:129]
	v_mfma_f32_16x16x32_bf16 v[122:125], v[144:147], v[168:171], v[122:125]
	v_mfma_f32_16x16x32_bf16 v[118:121], v[136:139], v[176:179], v[118:121]
	v_mfma_f32_16x16x32_bf16 v[114:117], v[144:147], v[176:179], v[114:117]
	v_mfma_f32_16x16x32_bf16 v[106:109], v[136:139], v[184:187], v[106:109]
	v_mfma_f32_16x16x32_bf16 v[98:101], v[144:147], v[184:187], v[98:101]
	v_mfma_f32_16x16x32_bf16 v[88:91], v[136:139], v[192:195], v[88:91]
	v_mfma_f32_16x16x32_bf16 v[80:83], v[144:147], v[192:195], v[80:83]
	v_mfma_f32_16x16x32_bf16 v[126:129], v[140:143], v[172:175], v[126:129]
	v_mfma_f32_16x16x32_bf16 v[122:125], v[148:151], v[172:175], v[122:125]
	v_mfma_f32_16x16x32_bf16 v[118:121], v[140:143], v[180:183], v[118:121]
	v_mfma_f32_16x16x32_bf16 v[114:117], v[148:151], v[180:183], v[114:117]
	v_mfma_f32_16x16x32_bf16 v[106:109], v[140:143], v[188:191], v[106:109]
	v_mfma_f32_16x16x32_bf16 v[98:101], v[148:151], v[188:191], v[98:101]
	v_mfma_f32_16x16x32_bf16 v[88:91], v[140:143], v[202:205], v[88:91]
	v_mfma_f32_16x16x32_bf16 v[80:83], v[148:151], v[202:205], v[80:83]
	s_setprio 0
	s_setprio 1
	v_mfma_f32_16x16x32_bf16 v[110:113], v[152:155], v[168:171], v[110:113]
	v_mfma_f32_16x16x32_bf16 v[102:105], v[160:163], v[168:171], v[102:105]
	v_mfma_f32_16x16x32_bf16 v[92:95], v[152:155], v[176:179], v[92:95]
	v_mfma_f32_16x16x32_bf16 v[84:87], v[160:163], v[176:179], v[84:87]
	v_mfma_f32_16x16x32_bf16 v[76:79], v[152:155], v[184:187], v[76:79]
	v_mfma_f32_16x16x32_bf16 v[72:75], v[160:163], v[184:187], v[72:75]
	v_mfma_f32_16x16x32_bf16 v[68:71], v[152:155], v[192:195], v[68:71]
	v_mfma_f32_16x16x32_bf16 v[64:67], v[160:163], v[192:195], v[64:67]
	v_mfma_f32_16x16x32_bf16 v[110:113], v[156:159], v[172:175], v[110:113]
	v_mfma_f32_16x16x32_bf16 v[102:105], v[164:167], v[172:175], v[102:105]
	v_mfma_f32_16x16x32_bf16 v[92:95], v[156:159], v[180:183], v[92:95]
	v_mfma_f32_16x16x32_bf16 v[84:87], v[164:167], v[180:183], v[84:87]
	v_mfma_f32_16x16x32_bf16 v[76:79], v[156:159], v[188:191], v[76:79]
	v_mfma_f32_16x16x32_bf16 v[72:75], v[164:167], v[188:191], v[72:75]
	v_mfma_f32_16x16x32_bf16 v[68:71], v[156:159], v[202:205], v[68:71]
	v_mfma_f32_16x16x32_bf16 v[64:67], v[164:167], v[202:205], v[64:67]
	s_setprio 0
	s_barrier
	s_mov_b32 m0, s40
	v_lshl_add_u64 v[198:199], s[74:75], 0, v[96:97]
	ds_read_b128 v[168:171], v135 offset:16384
	ds_read_b128 v[172:175], v135 offset:17408
	ds_read_b128 v[176:179], v135 offset:18432
	ds_read_b128 v[180:183], v135 offset:19456
	ds_read_b128 v[184:187], v135 offset:20480
	ds_read_b128 v[188:191], v135 offset:21504
	ds_read_b128 v[192:195], v135 offset:22528
	ds_read_b128 v[202:205], v135 offset:23552
	global_load_lds_dwordx4 v[198:199], off
	v_lshl_add_u64 v[200:201], s[74:75], 0, v[130:131]
	s_mov_b32 m0, s23
	v_lshl_add_u64 v[206:207], s[82:83], 0, v[96:97]
	global_load_lds_dwordx4 v[200:201], off
	s_mov_b32 m0, s37
	v_lshl_add_u64 v[208:209], s[72:73], 0, v[130:131]
	global_load_lds_dwordx4 v[206:207], off
	v_lshl_add_u64 v[206:207], s[82:83], 0, v[130:131]
	s_mov_b32 m0, s36
	s_nop 0
	global_load_lds_dwordx4 v[206:207], off
	v_lshl_add_u64 v[206:207], s[72:73], 0, v[96:97]
	s_mov_b32 m0, s5
	s_nop 0
	global_load_lds_dwordx4 v[206:207], off
	s_mov_b32 m0, s7
	s_nop 0
	global_load_lds_dwordx4 v[208:209], off
	s_setprio 1
	s_waitcnt vmcnt(8)
	s_waitcnt lgkmcnt(0)
	s_barrier
	v_mfma_f32_16x16x32_bf16 v[60:63], v[136:139], v[168:171], v[60:63]
	v_mfma_f32_16x16x32_bf16 v[56:59], v[144:147], v[168:171], v[56:59]
	v_mfma_f32_16x16x32_bf16 v[52:55], v[136:139], v[176:179], v[52:55]
	v_mfma_f32_16x16x32_bf16 v[48:51], v[144:147], v[176:179], v[48:51]
	v_mfma_f32_16x16x32_bf16 v[36:39], v[136:139], v[184:187], v[36:39]
	v_mfma_f32_16x16x32_bf16 v[32:35], v[144:147], v[184:187], v[32:35]
	v_mfma_f32_16x16x32_bf16 v[20:23], v[136:139], v[192:195], v[20:23]
	v_mfma_f32_16x16x32_bf16 v[16:19], v[144:147], v[192:195], v[16:19]
	v_mfma_f32_16x16x32_bf16 v[60:63], v[140:143], v[172:175], v[60:63]
	v_mfma_f32_16x16x32_bf16 v[56:59], v[148:151], v[172:175], v[56:59]
	v_mfma_f32_16x16x32_bf16 v[52:55], v[140:143], v[180:183], v[52:55]
	v_mfma_f32_16x16x32_bf16 v[48:51], v[148:151], v[180:183], v[48:51]
	v_mfma_f32_16x16x32_bf16 v[36:39], v[140:143], v[188:191], v[36:39]
	v_mfma_f32_16x16x32_bf16 v[32:35], v[148:151], v[188:191], v[32:35]
	v_mfma_f32_16x16x32_bf16 v[20:23], v[140:143], v[202:205], v[20:23]
	v_mfma_f32_16x16x32_bf16 v[16:19], v[148:151], v[202:205], v[16:19]
	s_setprio 0
	s_setprio 1
	v_mfma_f32_16x16x32_bf16 v[44:47], v[152:155], v[168:171], v[44:47]
	v_mfma_f32_16x16x32_bf16 v[40:43], v[160:163], v[168:171], v[40:43]
	v_mfma_f32_16x16x32_bf16 v[28:31], v[152:155], v[176:179], v[28:31]
	v_mfma_f32_16x16x32_bf16 v[24:27], v[160:163], v[176:179], v[24:27]
	v_mfma_f32_16x16x32_bf16 v[12:15], v[152:155], v[184:187], v[12:15]
	v_mfma_f32_16x16x32_bf16 v[8:11], v[160:163], v[184:187], v[8:11]
	v_mfma_f32_16x16x32_bf16 v[4:7], v[152:155], v[192:195], v[4:7]
	v_mfma_f32_16x16x32_bf16 v[0:3], v[160:163], v[192:195], v[0:3]
	v_mfma_f32_16x16x32_bf16 v[44:47], v[156:159], v[172:175], v[44:47]
	v_mfma_f32_16x16x32_bf16 v[40:43], v[164:167], v[172:175], v[40:43]
	v_mfma_f32_16x16x32_bf16 v[28:31], v[156:159], v[180:183], v[28:31]
	v_mfma_f32_16x16x32_bf16 v[24:27], v[164:167], v[180:183], v[24:27]
	v_mfma_f32_16x16x32_bf16 v[12:15], v[156:159], v[188:191], v[12:15]
	v_mfma_f32_16x16x32_bf16 v[8:11], v[164:167], v[188:191], v[8:11]
	v_mfma_f32_16x16x32_bf16 v[4:7], v[156:159], v[202:205], v[4:7]
	v_mfma_f32_16x16x32_bf16 v[0:3], v[164:167], v[202:205], v[0:3]
	s_setprio 0
	s_barrier
	v_add_u32_e32 v148, s13, v132
	v_add_u32_e32 v164, s6, v132
	ds_read_b128 v[136:139], v148
	ds_read_b128 v[140:143], v148 offset:1024
	ds_read_b128 v[144:147], v148 offset:2048
	ds_read_b128 v[148:151], v148 offset:3072
	ds_read_b128 v[152:155], v164
	ds_read_b128 v[156:159], v164 offset:1024
	ds_read_b128 v[160:163], v164 offset:2048
	ds_read_b128 v[164:167], v164 offset:3072
	s_mov_b32 m0, s15
	v_lshl_add_u64 v[214:215], s[62:63], 0, v[96:97]
	ds_read_b128 v[168:171], v135 offset:32768
	ds_read_b128 v[172:175], v135 offset:33792
	ds_read_b128 v[176:179], v135 offset:34816
	ds_read_b128 v[180:183], v135 offset:35840
	ds_read_b128 v[184:187], v135 offset:36864
	ds_read_b128 v[188:191], v135 offset:37888
	ds_read_b128 v[192:195], v135 offset:38912
	ds_read_b128 v[202:205], v135 offset:39936
	global_load_lds_dwordx4 v[214:215], off
	v_lshl_add_u64 v[214:215], s[62:63], 0, v[130:131]
	s_mov_b32 m0, s17
	s_nop 0
	global_load_lds_dwordx4 v[214:215], off
	s_setprio 1
	s_waitcnt vmcnt(8)
	s_waitcnt lgkmcnt(0)
	s_barrier
	v_mfma_f32_16x16x32_bf16 v[126:129], v[136:139], v[168:171], v[126:129]
	v_mfma_f32_16x16x32_bf16 v[122:125], v[144:147], v[168:171], v[122:125]
	v_mfma_f32_16x16x32_bf16 v[118:121], v[136:139], v[176:179], v[118:121]
	v_mfma_f32_16x16x32_bf16 v[114:117], v[144:147], v[176:179], v[114:117]
	v_mfma_f32_16x16x32_bf16 v[106:109], v[136:139], v[184:187], v[106:109]
	v_mfma_f32_16x16x32_bf16 v[98:101], v[144:147], v[184:187], v[98:101]
	v_mfma_f32_16x16x32_bf16 v[88:91], v[136:139], v[192:195], v[88:91]
	v_mfma_f32_16x16x32_bf16 v[80:83], v[144:147], v[192:195], v[80:83]
	v_mfma_f32_16x16x32_bf16 v[126:129], v[140:143], v[172:175], v[126:129]
	v_mfma_f32_16x16x32_bf16 v[122:125], v[148:151], v[172:175], v[122:125]
	v_mfma_f32_16x16x32_bf16 v[118:121], v[140:143], v[180:183], v[118:121]
	v_mfma_f32_16x16x32_bf16 v[114:117], v[148:151], v[180:183], v[114:117]
	v_mfma_f32_16x16x32_bf16 v[106:109], v[140:143], v[188:191], v[106:109]
	v_mfma_f32_16x16x32_bf16 v[98:101], v[148:151], v[188:191], v[98:101]
	v_mfma_f32_16x16x32_bf16 v[88:91], v[140:143], v[202:205], v[88:91]
	v_mfma_f32_16x16x32_bf16 v[80:83], v[148:151], v[202:205], v[80:83]
	s_setprio 0
	s_setprio 1
	v_mfma_f32_16x16x32_bf16 v[110:113], v[152:155], v[168:171], v[110:113]
	v_mfma_f32_16x16x32_bf16 v[102:105], v[160:163], v[168:171], v[102:105]
	v_mfma_f32_16x16x32_bf16 v[92:95], v[152:155], v[176:179], v[92:95]
	v_mfma_f32_16x16x32_bf16 v[84:87], v[160:163], v[176:179], v[84:87]
	v_mfma_f32_16x16x32_bf16 v[76:79], v[152:155], v[184:187], v[76:79]
	v_mfma_f32_16x16x32_bf16 v[72:75], v[160:163], v[184:187], v[72:75]
	v_mfma_f32_16x16x32_bf16 v[68:71], v[152:155], v[192:195], v[68:71]
	v_mfma_f32_16x16x32_bf16 v[64:67], v[160:163], v[192:195], v[64:67]
	v_mfma_f32_16x16x32_bf16 v[110:113], v[156:159], v[172:175], v[110:113]
	v_mfma_f32_16x16x32_bf16 v[102:105], v[164:167], v[172:175], v[102:105]
	v_mfma_f32_16x16x32_bf16 v[92:95], v[156:159], v[180:183], v[92:95]
	v_mfma_f32_16x16x32_bf16 v[84:87], v[164:167], v[180:183], v[84:87]
	v_mfma_f32_16x16x32_bf16 v[76:79], v[156:159], v[188:191], v[76:79]
	v_mfma_f32_16x16x32_bf16 v[72:75], v[164:167], v[188:191], v[72:75]
	v_mfma_f32_16x16x32_bf16 v[68:71], v[156:159], v[202:205], v[68:71]
	v_mfma_f32_16x16x32_bf16 v[64:67], v[164:167], v[202:205], v[64:67]
	s_setprio 0
	s_barrier
	s_mov_b32 m0, s3
	v_lshl_add_u64 v[198:199], v[198:199], 0, s[30:31]
	ds_read_b128 v[168:171], v135 offset:49152
	ds_read_b128 v[172:175], v135 offset:50176
	ds_read_b128 v[176:179], v135 offset:51200
	ds_read_b128 v[180:183], v135 offset:52224
	ds_read_b128 v[184:187], v135 offset:53248
	ds_read_b128 v[188:191], v135 offset:54272
	ds_read_b128 v[192:195], v135 offset:55296
	ds_read_b128 v[202:205], v135 offset:56320
	global_load_lds_dwordx4 v[198:199], off
	v_lshl_add_u64 v[198:199], v[200:201], 0, s[30:31]
	s_mov_b32 m0, s2
	s_nop 0
	global_load_lds_dwordx4 v[198:199], off
	v_lshl_add_u64 v[198:199], s[60:61], 0, v[96:97]
	s_mov_b32 m0, s49
	s_nop 0
	global_load_lds_dwordx4 v[198:199], off
	v_lshl_add_u64 v[198:199], s[60:61], 0, v[130:131]
	s_mov_b32 m0, s47
	s_nop 0
	global_load_lds_dwordx4 v[198:199], off
	v_lshl_add_u64 v[198:199], v[206:207], 0, s[30:31]
	s_mov_b32 m0, s18
	s_nop 0
	global_load_lds_dwordx4 v[198:199], off
	v_lshl_add_u64 v[198:199], v[208:209], 0, s[30:31]
	s_mov_b32 m0, s19
	s_nop 0
	global_load_lds_dwordx4 v[198:199], off
	s_setprio 1
	s_waitcnt vmcnt(8)
	s_waitcnt lgkmcnt(0)
	s_barrier
	v_mfma_f32_16x16x32_bf16 v[60:63], v[136:139], v[168:171], v[60:63]
	v_mfma_f32_16x16x32_bf16 v[56:59], v[144:147], v[168:171], v[56:59]
	v_mfma_f32_16x16x32_bf16 v[52:55], v[136:139], v[176:179], v[52:55]
	v_mfma_f32_16x16x32_bf16 v[48:51], v[144:147], v[176:179], v[48:51]
	v_mfma_f32_16x16x32_bf16 v[36:39], v[136:139], v[184:187], v[36:39]
	v_mfma_f32_16x16x32_bf16 v[32:35], v[144:147], v[184:187], v[32:35]
	v_mfma_f32_16x16x32_bf16 v[20:23], v[136:139], v[192:195], v[20:23]
	v_mfma_f32_16x16x32_bf16 v[16:19], v[144:147], v[192:195], v[16:19]
	v_mfma_f32_16x16x32_bf16 v[60:63], v[140:143], v[172:175], v[60:63]
	v_mfma_f32_16x16x32_bf16 v[56:59], v[148:151], v[172:175], v[56:59]
	v_mfma_f32_16x16x32_bf16 v[52:55], v[140:143], v[180:183], v[52:55]
	v_mfma_f32_16x16x32_bf16 v[48:51], v[148:151], v[180:183], v[48:51]
	v_mfma_f32_16x16x32_bf16 v[36:39], v[140:143], v[188:191], v[36:39]
	v_mfma_f32_16x16x32_bf16 v[32:35], v[148:151], v[188:191], v[32:35]
	v_mfma_f32_16x16x32_bf16 v[20:23], v[140:143], v[202:205], v[20:23]
	v_mfma_f32_16x16x32_bf16 v[16:19], v[148:151], v[202:205], v[16:19]
	s_setprio 0
	s_setprio 1
	v_mfma_f32_16x16x32_bf16 v[44:47], v[152:155], v[168:171], v[44:47]
	v_mfma_f32_16x16x32_bf16 v[40:43], v[160:163], v[168:171], v[40:43]
	v_mfma_f32_16x16x32_bf16 v[28:31], v[152:155], v[176:179], v[28:31]
	v_mfma_f32_16x16x32_bf16 v[24:27], v[160:163], v[176:179], v[24:27]
	v_mfma_f32_16x16x32_bf16 v[12:15], v[152:155], v[184:187], v[12:15]
	v_mfma_f32_16x16x32_bf16 v[8:11], v[160:163], v[184:187], v[8:11]
	v_mfma_f32_16x16x32_bf16 v[4:7], v[152:155], v[192:195], v[4:7]
	v_mfma_f32_16x16x32_bf16 v[0:3], v[160:163], v[192:195], v[0:3]
	v_mfma_f32_16x16x32_bf16 v[44:47], v[156:159], v[172:175], v[44:47]
	v_mfma_f32_16x16x32_bf16 v[40:43], v[164:167], v[172:175], v[40:43]
	v_mfma_f32_16x16x32_bf16 v[28:31], v[156:159], v[180:183], v[28:31]
	v_mfma_f32_16x16x32_bf16 v[24:27], v[164:167], v[180:183], v[24:27]
	v_mfma_f32_16x16x32_bf16 v[12:15], v[156:159], v[188:191], v[12:15]
	v_mfma_f32_16x16x32_bf16 v[8:11], v[164:167], v[188:191], v[8:11]
	v_mfma_f32_16x16x32_bf16 v[4:7], v[156:159], v[202:205], v[4:7]
	v_mfma_f32_16x16x32_bf16 v[0:3], v[164:167], v[202:205], v[0:3]
	s_setprio 0
	s_barrier
	s_nop 0
	s_nop 0
	s_nop 0
	s_nop 0
	s_movk_i32 s2, 0x100
	s_andn2_b64 vcc, exec, s[58:59]
	s_mov_b64 s[60:61], -1
	s_mov_b64 s[58:59], 0
	s_cbranch_vccz .LBB0_973
	s_and_b64 vcc, exec, s[38:39]
	s_cbranch_vccz .LBB0_976
	s_barrier
